# attention steps: canonicalising self-max pairs and +0 row-sum add removed (5 VALU per step)
# speedup vs baseline: 1.0009x; 1.0006x over previous
.LBB0_879:
	v_add_u32_e32 v186, s18, v240
	ds_read_b64_tr_b16 v[178:179], v186 offset:24576
	ds_read_b64_tr_b16 v[180:181], v186 offset:25088
	s_waitcnt lgkmcnt(9)
	v_mfma_f32_32x32x16_bf16 v[96:111], v[174:177], v[134:137], v[32:47]
	v_add_f32_e32 v80, v64, v65
	v_add_f32_e32 v80, v66, v80
	v_add_f32_e32 v80, v67, v80
	v_add_f32_e32 v80, v68, v80
	v_add_f32_e32 v80, v69, v80
	v_cvt_pk_bf16_f32 v142, v64, v65
	v_cvt_pk_bf16_f32 v143, v66, v67
	ds_read_b64_tr_b16 v[174:175], v186 offset:28672
	ds_read_b64_tr_b16 v[176:177], v186 offset:29184
	v_add_f32_e32 v64, v70, v80
	s_waitcnt lgkmcnt(10)
	v_mfma_f32_32x32x16_bf16 v[80:95], v[170:173], v[134:137], v[32:47]
	v_add_f32_e32 v64, v71, v64
	v_add_f32_e32 v64, v72, v64
	v_add_f32_e32 v126, v73, v64
	v_cvt_pk_bf16_f32 v144, v68, v69
	v_cvt_pk_bf16_f32 v145, v70, v71
	ds_read_b64_tr_b16 v[64:65], v186 offset:25600
	ds_read_b64_tr_b16 v[66:67], v186 offset:26112
	s_waitcnt lgkmcnt(11)
	v_mfma_f32_32x32x16_bf16 v[96:111], v[166:169], v[122:125], v[96:111]
	v_add_f32_e32 v68, v74, v126
	v_add_f32_e32 v68, v75, v68
	v_add_f32_e32 v68, v76, v68
	v_add_f32_e32 v126, v77, v68
	v_cvt_pk_bf16_f32 v138, v72, v73
	v_cvt_pk_bf16_f32 v139, v74, v75
	ds_read_b64_tr_b16 v[68:69], v186 offset:29696
	ds_read_b64_tr_b16 v[70:71], v186 offset:30208
	s_waitcnt lgkmcnt(12)
	v_mfma_f32_32x32x16_bf16 v[80:95], v[162:165], v[122:125], v[80:95]
	v_add_f32_e32 v72, v78, v126
	v_add_f32_e32 v72, v79, v72
	v_add_f32_e32 v72, v48, v72
	v_add_f32_e32 v126, v49, v72
	v_cvt_pk_bf16_f32 v140, v76, v77
	v_cvt_pk_bf16_f32 v141, v78, v79
	ds_read_b64_tr_b16 v[72:73], v186 offset:26624
	ds_read_b64_tr_b16 v[74:75], v186 offset:27136
	s_waitcnt lgkmcnt(13)
	v_mfma_f32_32x32x16_bf16 v[96:111], v[158:161], v[118:121], v[96:111]
	v_add_f32_e32 v76, v50, v126
	v_add_f32_e32 v76, v51, v76
	v_add_f32_e32 v76, v52, v76
	v_add_f32_e32 v76, v53, v76
	v_cvt_pk_bf16_f32 v130, v48, v49
	v_cvt_pk_bf16_f32 v131, v50, v51
	ds_read_b64_tr_b16 v[48:49], v186 offset:30720
	ds_read_b64_tr_b16 v[50:51], v186 offset:31232
	s_waitcnt lgkmcnt(14)
	v_mfma_f32_32x32x16_bf16 v[80:95], v[154:157], v[118:121], v[80:95]
	v_add_f32_e32 v76, v54, v76
	v_add_f32_e32 v76, v55, v76
	v_add_f32_e32 v76, v56, v76
	v_add_f32_e32 v76, v57, v76
	v_cvt_pk_bf16_f32 v132, v52, v53
	v_cvt_pk_bf16_f32 v133, v54, v55
	ds_read_b64_tr_b16 v[52:53], v186 offset:27648
	ds_read_b64_tr_b16 v[54:55], v186 offset:28160
	s_waitcnt lgkmcnt(14)
	v_mfma_f32_32x32x16_bf16 v[96:111], v[150:153], v[114:117], v[96:111]
	v_add_f32_e32 v76, v58, v76
	v_add_f32_e32 v76, v59, v76
	v_add_f32_e32 v76, v60, v76
	v_add_f32_e32 v76, v61, v76
	v_cvt_pk_bf16_f32 v126, v56, v57
	v_cvt_pk_bf16_f32 v127, v58, v59
	ds_read_b64_tr_b16 v[56:57], v186 offset:31744
	ds_read_b64_tr_b16 v[58:59], v186 offset:32256
	v_mfma_f32_32x32x16_bf16 v[80:95], v[146:149], v[114:117], v[80:95]
	v_add_f32_e32 v76, v62, v76
	v_add_f32_e32 v76, v63, v76
	v_cvt_pk_bf16_f32 v128, v60, v61
	v_cvt_pk_bf16_f32 v129, v62, v63
	v_lshl_add_u64 v[186:187], v[184:185], 0, s[8:9]
	v_lshl_add_u64 v[60:61], v[186:187], 0, s[86:87]
	v_lshl_add_u64 v[188:189], v[182:183], 0, s[8:9]
	s_add_i32 s18, s64, s35
	s_mov_b32 s19, m0
	s_mov_b32 m0, s18
	s_nop 0
	global_load_lds_dwordx4 v[60:61], off
	s_mov_b32 m0, s19
	v_lshl_add_u64 v[60:61], v[188:189], 0, s[88:89]
	s_add_i32 s18, s62, s58
	s_mov_b32 s19, m0
	s_mov_b32 m0, s18
	s_nop 0
	global_load_lds_dwordx4 v[60:61], off
	s_mov_b32 m0, s19
	v_max_f32_e32 v60, v96, v97
	v_max3_f32 v61, v98, v99, v81
	v_max3_f32 v60, v60, v80, v82
	v_max3_f32 v60, v60, v83, v100
	v_max3_f32 v61, v61, v102, v103
	v_max3_f32 v60, v60, v101, v84
	v_max3_f32 v61, v61, v86, v87
	v_max3_f32 v60, v60, v85, v104
	v_max3_f32 v61, v61, v106, v107
	v_max3_f32 v60, v60, v105, v88
	v_max3_f32 v61, v61, v90, v91
	v_max3_f32 v60, v60, v89, v108
	v_max3_f32 v61, v61, v110, v111
	v_max3_f32 v60, v60, v109, v92
	v_max3_f32 v61, v61, v94, v95
	v_max3_f32 v60, v60, v93, v61
	v_mov_b32_e32 v61, v60
	s_nop 1
	v_permlane32_swap_b32_e32 v60, v61
	v_max_f32_e32 v60, v60, v61
	v_cmp_lt_f32_e32 vcc, s34, v60
	s_cmp_lg_u64 vcc, 0
	v_add_f32_e32 v212, v241, v76
	s_cselect_b64 s[18:19], -1, 0
	s_cbranch_vccnz .LBB0_887

.LBB0_882:
	s_add_i32 s18, s62, 0x2000
	s_cmpk_lg_i32 s62, 0x4000
	s_cselect_b32 s60, s18, 0
	v_add_u32_e32 v213, s64, v240
	ds_read_b64_tr_b16 v[150:151], v213 offset:24576
	ds_read_b64_tr_b16 v[152:153], v213 offset:25088
	s_waitcnt lgkmcnt(9)
	v_mfma_f32_32x32x16_bf16 v[64:79], v[60:63], v[134:137], v[32:47]
	v_add_f32_e32 v48, v96, v97
	v_add_f32_e32 v48, v98, v48
	v_add_f32_e32 v48, v99, v48
	v_add_f32_e32 v48, v100, v48
	v_add_f32_e32 v48, v101, v48
	v_cvt_pk_bf16_f32 v142, v96, v97
	v_cvt_pk_bf16_f32 v143, v98, v99
	ds_read_b64_tr_b16 v[146:147], v213 offset:28672
	ds_read_b64_tr_b16 v[148:149], v213 offset:29184
	v_add_f32_e32 v48, v102, v48
	v_add_f32_e32 v48, v103, v48
	v_add_f32_e32 v48, v104, v48
	v_add_f32_e32 v126, v105, v48
	s_waitcnt lgkmcnt(10)
	v_mfma_f32_32x32x16_bf16 v[48:63], v[174:177], v[134:137], v[32:47]
	v_cvt_pk_bf16_f32 v144, v100, v101
	v_cvt_pk_bf16_f32 v145, v102, v103
	ds_read_b64_tr_b16 v[96:97], v213 offset:25600
	ds_read_b64_tr_b16 v[98:99], v213 offset:26112
	s_waitcnt lgkmcnt(11)
	v_mfma_f32_32x32x16_bf16 v[64:79], v[178:181], v[122:125], v[64:79]
	v_add_f32_e32 v100, v106, v126
	v_add_f32_e32 v100, v107, v100
	v_add_f32_e32 v100, v108, v100
	v_add_f32_e32 v126, v109, v100
	v_cvt_pk_bf16_f32 v138, v104, v105
	v_cvt_pk_bf16_f32 v139, v106, v107
	ds_read_b64_tr_b16 v[100:101], v213 offset:29696
	ds_read_b64_tr_b16 v[102:103], v213 offset:30208
	s_waitcnt lgkmcnt(12)
	v_mfma_f32_32x32x16_bf16 v[48:63], v[170:173], v[122:125], v[48:63]
	v_add_f32_e32 v104, v110, v126
	v_add_f32_e32 v104, v111, v104
	v_add_f32_e32 v104, v80, v104
	v_add_f32_e32 v126, v81, v104
	v_cvt_pk_bf16_f32 v140, v108, v109
	v_cvt_pk_bf16_f32 v141, v110, v111
	ds_read_b64_tr_b16 v[104:105], v213 offset:26624
	ds_read_b64_tr_b16 v[106:107], v213 offset:27136
	s_waitcnt lgkmcnt(13)
	v_mfma_f32_32x32x16_bf16 v[64:79], v[166:169], v[118:121], v[64:79]
	v_add_f32_e32 v108, v82, v126
	v_add_f32_e32 v108, v83, v108
	v_add_f32_e32 v108, v84, v108
	v_add_f32_e32 v108, v85, v108
	v_cvt_pk_bf16_f32 v130, v80, v81
	v_cvt_pk_bf16_f32 v131, v82, v83
	ds_read_b64_tr_b16 v[80:81], v213 offset:30720
	ds_read_b64_tr_b16 v[82:83], v213 offset:31232
	s_waitcnt lgkmcnt(14)
	v_mfma_f32_32x32x16_bf16 v[48:63], v[162:165], v[118:121], v[48:63]
	v_add_f32_e32 v108, v86, v108
	v_add_f32_e32 v108, v87, v108
	v_add_f32_e32 v108, v88, v108
	v_add_f32_e32 v108, v89, v108
	v_cvt_pk_bf16_f32 v132, v84, v85
	v_cvt_pk_bf16_f32 v133, v86, v87
	ds_read_b64_tr_b16 v[84:85], v213 offset:27648
	ds_read_b64_tr_b16 v[86:87], v213 offset:28160
	s_waitcnt lgkmcnt(14)
	v_mfma_f32_32x32x16_bf16 v[64:79], v[158:161], v[114:117], v[64:79]
	v_add_f32_e32 v108, v90, v108
	v_add_f32_e32 v108, v91, v108
	v_add_f32_e32 v108, v92, v108
	v_add_f32_e32 v108, v93, v108
	v_cvt_pk_bf16_f32 v126, v88, v89
	v_cvt_pk_bf16_f32 v127, v90, v91
	ds_read_b64_tr_b16 v[88:89], v213 offset:31744
	ds_read_b64_tr_b16 v[90:91], v213 offset:32256
	v_mfma_f32_32x32x16_bf16 v[48:63], v[154:157], v[114:117], v[48:63]
	v_add_f32_e32 v108, v94, v108
	v_add_f32_e32 v108, v95, v108
	v_cvt_pk_bf16_f32 v128, v92, v93
	v_cvt_pk_bf16_f32 v129, v94, v95
	s_mov_b64 s[18:19], 0xbaa0000
	v_lshl_add_u64 v[92:93], v[186:187], 0, s[18:19]
	s_add_i32 s18, s62, s35
	s_mov_b32 s19, m0
	s_mov_b32 m0, s18
	s_nop 0
	global_load_lds_dwordx4 v[92:93], off
	s_mov_b32 m0, s19
	s_mov_b64 s[18:19], 0xfa60000
	v_lshl_add_u64 v[92:93], v[188:189], 0, s[18:19]
	s_add_i32 s18, s60, s58
	s_mov_b32 s19, m0
	s_mov_b32 m0, s18
	s_nop 0
	global_load_lds_dwordx4 v[92:93], off
	s_mov_b32 m0, s19
	v_max_f32_e32 v92, v64, v65
	v_max3_f32 v93, v66, v67, v49
	v_max3_f32 v92, v92, v48, v50
	v_max3_f32 v92, v92, v51, v68
	v_max3_f32 v93, v93, v70, v71
	v_max3_f32 v92, v92, v69, v52
	v_max3_f32 v93, v93, v54, v55
	v_max3_f32 v92, v92, v53, v72
	v_max3_f32 v93, v93, v74, v75
	v_max3_f32 v92, v92, v73, v56
	v_max3_f32 v93, v93, v58, v59
	v_max3_f32 v92, v92, v57, v76
	v_max3_f32 v93, v93, v78, v79
	v_max3_f32 v92, v92, v77, v60
	v_max3_f32 v93, v93, v62, v63
	v_max3_f32 v92, v92, v61, v93
	v_mov_b32_e32 v93, v92
	s_nop 1
	v_permlane32_swap_b32_e32 v92, v93
	v_max_f32_e32 v92, v92, v93
	v_cmp_lt_f32_e32 vcc, s34, v92
	s_cmp_lg_u64 vcc, 0
	v_add_f32_e32 v241, v212, v108
	s_cselect_b64 s[18:19], -1, 0
	s_cbranch_vccnz .LBB0_890

.LBB0_895:
	v_add_u32_e32 v112, s61, v240
	ds_read_b64_tr_b16 v[100:101], v112 offset:24576
	ds_read_b64_tr_b16 v[102:103], v112 offset:25088
	v_add_f32_e32 v80, v64, v65
	v_add_f32_e32 v80, v66, v80
	v_add_f32_e32 v80, v67, v80
	v_add_f32_e32 v80, v68, v80
	v_add_f32_e32 v104, v69, v80
	s_waitcnt lgkmcnt(9)
	v_mfma_f32_32x32x16_bf16 v[80:95], v[174:177], v[134:137], v[32:47]
	v_cvt_pk_bf16_f32 v142, v64, v65
	v_cvt_pk_bf16_f32 v143, v66, v67
	ds_read_b64_tr_b16 v[96:97], v112 offset:28672
	ds_read_b64_tr_b16 v[98:99], v112 offset:29184
	s_waitcnt lgkmcnt(10)
	v_mfma_f32_32x32x16_bf16 v[32:47], v[170:173], v[134:137], v[32:47]
	v_add_f32_e32 v64, v70, v104
	v_add_f32_e32 v64, v71, v64
	v_add_f32_e32 v64, v72, v64
	v_add_f32_e32 v64, v73, v64
	v_cvt_pk_bf16_f32 v144, v68, v69
	v_cvt_pk_bf16_f32 v145, v70, v71
	ds_read_b64_tr_b16 v[104:105], v112 offset:25600
	ds_read_b64_tr_b16 v[106:107], v112 offset:26112
	s_waitcnt lgkmcnt(11)
	v_mfma_f32_32x32x16_bf16 v[80:95], v[166:169], v[122:125], v[80:95]
	v_add_f32_e32 v64, v74, v64
	v_add_f32_e32 v64, v75, v64
	v_add_f32_e32 v64, v76, v64
	v_add_f32_e32 v64, v77, v64
	v_cvt_pk_bf16_f32 v138, v72, v73
	v_cvt_pk_bf16_f32 v139, v74, v75
	ds_read_b64_tr_b16 v[108:109], v112 offset:29696
	ds_read_b64_tr_b16 v[110:111], v112 offset:30208
	s_waitcnt lgkmcnt(12)
	v_mfma_f32_32x32x16_bf16 v[32:47], v[162:165], v[122:125], v[32:47]
	v_add_f32_e32 v64, v78, v64
	v_add_f32_e32 v64, v79, v64
	v_add_f32_e32 v64, v48, v64
	v_add_f32_e32 v64, v49, v64
	v_cvt_pk_bf16_f32 v140, v76, v77
	v_cvt_pk_bf16_f32 v141, v78, v79
	ds_read_b64_tr_b16 v[122:123], v112 offset:26624
	ds_read_b64_tr_b16 v[124:125], v112 offset:27136
	s_waitcnt lgkmcnt(13)
	v_mfma_f32_32x32x16_bf16 v[80:95], v[158:161], v[118:121], v[80:95]
	v_add_f32_e32 v64, v50, v64
	v_add_f32_e32 v64, v51, v64
	v_add_f32_e32 v64, v52, v64
	v_add_f32_e32 v64, v53, v64
	v_cvt_pk_bf16_f32 v130, v48, v49
	v_cvt_pk_bf16_f32 v131, v50, v51
	ds_read_b64_tr_b16 v[134:135], v112 offset:30720
	ds_read_b64_tr_b16 v[136:137], v112 offset:31232
	s_waitcnt lgkmcnt(14)
	v_mfma_f32_32x32x16_bf16 v[32:47], v[154:157], v[118:121], v[32:47]
	v_add_f32_e32 v48, v54, v64
	v_add_f32_e32 v48, v55, v48
	v_add_f32_e32 v48, v56, v48
	v_add_f32_e32 v48, v57, v48
	v_cvt_pk_bf16_f32 v132, v52, v53
	v_cvt_pk_bf16_f32 v133, v54, v55
	ds_read_b64_tr_b16 v[118:119], v112 offset:27648
	ds_read_b64_tr_b16 v[120:121], v112 offset:28160
	s_waitcnt lgkmcnt(14)
	v_mfma_f32_32x32x16_bf16 v[80:95], v[150:153], v[114:117], v[80:95]
	v_add_f32_e32 v48, v58, v48
	v_add_f32_e32 v48, v59, v48
	v_add_f32_e32 v48, v60, v48
	v_add_f32_e32 v48, v61, v48
	v_cvt_pk_bf16_f32 v126, v56, v57
	v_cvt_pk_bf16_f32 v127, v58, v59
	ds_read_b64_tr_b16 v[150:151], v112 offset:31744
	ds_read_b64_tr_b16 v[152:153], v112 offset:32256
	v_mfma_f32_32x32x16_bf16 v[32:47], v[146:149], v[114:117], v[32:47]
	v_add_f32_e32 v48, v62, v48
	v_add_f32_e32 v48, v63, v48
	v_add_f32_e32 v64, 0, v48
	v_cvt_pk_bf16_f32 v128, v60, v61
	v_cvt_pk_bf16_f32 v129, v62, v63
	v_or_b32_e32 v49, 0xe0, v235
	v_or_b32_e32 v48, 0xc0, v235
	v_cmp_le_i32_e32 vcc, v49, v237
	v_or_b32_e32 v50, 0xe1, v235
	v_or_b32_e32 v51, 0xe2, v235
	s_nop 1
	v_cndmask_b32_e32 v32, v223, v32, vcc
	v_cmp_lt_i32_e32 vcc, v48, v237
	v_or_b32_e32 v52, 0xe3, v235
	v_or_b32_e32 v53, 0xe8, v235
	v_cndmask_b32_e32 v49, v223, v81, vcc
	v_cmp_le_i32_e32 vcc, v48, v237
	v_or_b32_e32 v54, 0xe9, v235
	v_or_b32_e32 v55, 0xea, v235
	v_cndmask_b32_e32 v48, v223, v80, vcc
	v_cmp_le_i32_e32 vcc, v50, v237
	v_or_b32_e32 v50, 0xc2, v235
	v_or_b32_e32 v56, 0xeb, v235
	v_cndmask_b32_e32 v33, v223, v33, vcc
	v_cmp_le_i32_e32 vcc, v50, v237
	v_or_b32_e32 v57, 0xf0, v235
	v_or_b32_e32 v58, 0xf1, v235
	v_cndmask_b32_e32 v50, v223, v82, vcc
	v_cmp_le_i32_e32 vcc, v51, v237
	v_or_b32_e32 v51, 0xc3, v235
	v_or_b32_e32 v59, 0xf2, v235
	v_cndmask_b32_e32 v34, v223, v34, vcc
	v_cmp_le_i32_e32 vcc, v51, v237
	v_or_b32_e32 v60, 0xf3, v235
	v_or_b32_e32 v61, 0xf8, v235
	v_cndmask_b32_e32 v51, v223, v83, vcc
	v_cmp_le_i32_e32 vcc, v52, v237
	v_or_b32_e32 v52, 0xc8, v235
	v_or_b32_e32 v62, 0xf9, v235
	v_cndmask_b32_e32 v35, v223, v35, vcc
	v_cmp_le_i32_e32 vcc, v52, v237
	v_or_b32_e32 v63, 0xfa, v235
	v_or_b32_e32 v65, 0xfb, v235
	v_cndmask_b32_e32 v52, v223, v84, vcc
	v_cmp_le_i32_e32 vcc, v53, v237
	v_or_b32_e32 v53, 0xc9, v235
	v_max_f32_e32 v66, v48, v48
	v_cndmask_b32_e32 v36, v223, v36, vcc
	v_cmp_le_i32_e32 vcc, v53, v237
	v_add_f32_e32 v80, v241, v64
	s_nop 0
	v_cndmask_b32_e32 v53, v223, v85, vcc
	v_cmp_le_i32_e32 vcc, v54, v237
	v_or_b32_e32 v54, 0xca, v235
	s_nop 0
	v_cndmask_b32_e32 v37, v223, v37, vcc
	v_cmp_le_i32_e32 vcc, v54, v237
	s_nop 1
	v_cndmask_b32_e32 v54, v223, v86, vcc
	v_cmp_le_i32_e32 vcc, v55, v237
	v_or_b32_e32 v55, 0xcb, v235
	s_nop 0
	v_cndmask_b32_e32 v38, v223, v38, vcc
	v_cmp_le_i32_e32 vcc, v55, v237
	s_nop 1
	v_cndmask_b32_e32 v55, v223, v87, vcc
	v_cmp_le_i32_e32 vcc, v56, v237
	v_or_b32_e32 v56, 0xd0, v235
	s_nop 0
	v_cndmask_b32_e32 v39, v223, v39, vcc
	v_cmp_le_i32_e32 vcc, v56, v237
	s_nop 1
	v_cndmask_b32_e32 v56, v223, v88, vcc
	v_cmp_le_i32_e32 vcc, v57, v237
	v_or_b32_e32 v57, 0xd1, v235
	s_nop 0
	v_cndmask_b32_e32 v40, v223, v40, vcc
	v_cmp_le_i32_e32 vcc, v57, v237
	s_nop 1
	v_cndmask_b32_e32 v57, v223, v89, vcc
	v_cmp_le_i32_e32 vcc, v58, v237
	v_or_b32_e32 v58, 0xd2, v235
	s_nop 0
	v_cndmask_b32_e32 v41, v223, v41, vcc
	v_cmp_le_i32_e32 vcc, v58, v237
	s_nop 1
	v_cndmask_b32_e32 v58, v223, v90, vcc
	v_cmp_le_i32_e32 vcc, v59, v237
	v_or_b32_e32 v59, 0xd3, v235
	s_nop 0
	v_cndmask_b32_e32 v42, v223, v42, vcc
	v_cmp_le_i32_e32 vcc, v59, v237
	s_nop 1
	v_cndmask_b32_e32 v59, v223, v91, vcc
	v_cmp_le_i32_e32 vcc, v60, v237
	v_or_b32_e32 v60, 0xd8, v235
	s_nop 0
	v_cndmask_b32_e32 v43, v223, v43, vcc
	v_cmp_le_i32_e32 vcc, v60, v237
	s_nop 1
	v_cndmask_b32_e32 v60, v223, v92, vcc
	v_cmp_le_i32_e32 vcc, v61, v237
	v_or_b32_e32 v61, 0xd9, v235
	s_nop 0
	v_cndmask_b32_e32 v44, v223, v44, vcc
	v_cmp_le_i32_e32 vcc, v61, v237
	s_nop 1
	v_cndmask_b32_e32 v61, v223, v93, vcc
	v_cmp_le_i32_e32 vcc, v62, v237
	v_or_b32_e32 v62, 0xda, v235
	s_nop 0
	v_cndmask_b32_e32 v45, v223, v45, vcc
	v_cmp_le_i32_e32 vcc, v62, v237
	s_nop 1
	v_cndmask_b32_e32 v62, v223, v94, vcc
	v_cmp_le_i32_e32 vcc, v63, v237
	v_or_b32_e32 v63, 0xdb, v235
	s_nop 0
	v_cndmask_b32_e32 v46, v223, v46, vcc
	v_cmp_le_i32_e32 vcc, v63, v237
	s_nop 1
	v_cndmask_b32_e32 v63, v223, v95, vcc
	v_cmp_le_i32_e32 vcc, v65, v237
	v_max_f32_e32 v65, v49, v49
	v_max_f32_e32 v65, v66, v65
	v_max3_f32 v66, v50, v51, v33
	v_max3_f32 v65, v65, v32, v34
	v_max3_f32 v65, v65, v35, v52
	v_max3_f32 v66, v66, v54, v55
	v_max3_f32 v65, v65, v53, v36
	v_max3_f32 v66, v66, v38, v39
	v_max3_f32 v65, v65, v37, v56
	v_max3_f32 v66, v66, v58, v59
	v_max3_f32 v65, v65, v57, v40
	v_max3_f32 v66, v66, v42, v43
	v_cndmask_b32_e32 v47, v223, v47, vcc
	v_max3_f32 v65, v65, v41, v60
	v_max3_f32 v66, v66, v62, v63
	v_max3_f32 v65, v65, v61, v44
	v_max3_f32 v66, v66, v46, v47
	v_max3_f32 v64, v65, v45, v66
	v_mov_b32_e32 v65, v64
	s_nop 1
	v_permlane32_swap_b32_e32 v64, v65
	v_max_f32_e32 v64, v64, v65
	v_cmp_lt_f32_e32 vcc, s34, v64
	s_cmp_lg_u64 vcc, 0
	s_cselect_b64 s[0:1], -1, 0
	s_cbranch_vccnz .LBB0_950

.LBB0_902:
	v_add_u32_e32 v182, s62, v240
	ds_read_b64_tr_b16 v[178:179], v182 offset:24576
	ds_read_b64_tr_b16 v[180:181], v182 offset:25088
	s_waitcnt lgkmcnt(9)
	v_mfma_f32_32x32x16_bf16 v[96:111], v[174:177], v[134:137], v[32:47]
	v_add_f32_e32 v80, v64, v65
	v_add_f32_e32 v80, v66, v80
	v_add_f32_e32 v80, v67, v80
	v_add_f32_e32 v80, v68, v80
	v_add_f32_e32 v80, v69, v80
	v_cvt_pk_bf16_f32 v142, v64, v65
	v_cvt_pk_bf16_f32 v143, v66, v67
	ds_read_b64_tr_b16 v[174:175], v182 offset:28672
	ds_read_b64_tr_b16 v[176:177], v182 offset:29184
	v_add_f32_e32 v64, v70, v80
	s_waitcnt lgkmcnt(10)
	v_mfma_f32_32x32x16_bf16 v[80:95], v[170:173], v[134:137], v[32:47]
	v_add_f32_e32 v64, v71, v64
	v_add_f32_e32 v64, v72, v64
	v_add_f32_e32 v126, v73, v64
	v_cvt_pk_bf16_f32 v144, v68, v69
	v_cvt_pk_bf16_f32 v145, v70, v71
	ds_read_b64_tr_b16 v[64:65], v182 offset:25600
	ds_read_b64_tr_b16 v[66:67], v182 offset:26112
	s_waitcnt lgkmcnt(11)
	v_mfma_f32_32x32x16_bf16 v[96:111], v[166:169], v[122:125], v[96:111]
	v_add_f32_e32 v68, v74, v126
	v_add_f32_e32 v68, v75, v68
	v_add_f32_e32 v68, v76, v68
	v_add_f32_e32 v126, v77, v68
	v_cvt_pk_bf16_f32 v138, v72, v73
	v_cvt_pk_bf16_f32 v139, v74, v75
	ds_read_b64_tr_b16 v[68:69], v182 offset:29696
	ds_read_b64_tr_b16 v[70:71], v182 offset:30208
	s_waitcnt lgkmcnt(12)
	v_mfma_f32_32x32x16_bf16 v[80:95], v[162:165], v[122:125], v[80:95]
	v_add_f32_e32 v72, v78, v126
	v_add_f32_e32 v72, v79, v72
	v_add_f32_e32 v72, v48, v72
	v_add_f32_e32 v126, v49, v72
	v_cvt_pk_bf16_f32 v140, v76, v77
	v_cvt_pk_bf16_f32 v141, v78, v79
	ds_read_b64_tr_b16 v[72:73], v182 offset:26624
	ds_read_b64_tr_b16 v[74:75], v182 offset:27136
	s_waitcnt lgkmcnt(13)
	v_mfma_f32_32x32x16_bf16 v[96:111], v[158:161], v[118:121], v[96:111]
	v_add_f32_e32 v76, v50, v126
	v_add_f32_e32 v76, v51, v76
	v_add_f32_e32 v76, v52, v76
	v_add_f32_e32 v76, v53, v76
	v_cvt_pk_bf16_f32 v130, v48, v49
	v_cvt_pk_bf16_f32 v131, v50, v51
	ds_read_b64_tr_b16 v[48:49], v182 offset:30720
	ds_read_b64_tr_b16 v[50:51], v182 offset:31232
	s_waitcnt lgkmcnt(14)
	v_mfma_f32_32x32x16_bf16 v[80:95], v[154:157], v[118:121], v[80:95]
	v_add_f32_e32 v76, v54, v76
	v_add_f32_e32 v76, v55, v76
	v_add_f32_e32 v76, v56, v76
	v_add_f32_e32 v76, v57, v76
	v_cvt_pk_bf16_f32 v132, v52, v53
	v_cvt_pk_bf16_f32 v133, v54, v55
	ds_read_b64_tr_b16 v[52:53], v182 offset:27648
	ds_read_b64_tr_b16 v[54:55], v182 offset:28160
	s_waitcnt lgkmcnt(14)
	v_mfma_f32_32x32x16_bf16 v[96:111], v[150:153], v[114:117], v[96:111]
	v_add_f32_e32 v76, v58, v76
	v_add_f32_e32 v76, v59, v76
	v_add_f32_e32 v76, v60, v76
	v_add_f32_e32 v76, v61, v76
	v_cvt_pk_bf16_f32 v126, v56, v57
	v_cvt_pk_bf16_f32 v127, v58, v59
	ds_read_b64_tr_b16 v[56:57], v182 offset:31744
	ds_read_b64_tr_b16 v[58:59], v182 offset:32256
	v_mfma_f32_32x32x16_bf16 v[80:95], v[146:149], v[114:117], v[80:95]
	v_add_f32_e32 v76, v62, v76
	v_add_f32_e32 v76, v63, v76
	v_cvt_pk_bf16_f32 v128, v60, v61
	v_cvt_pk_bf16_f32 v129, v62, v63
	s_add_i32 s0, s20, 1
	s_cmp_ge_u32 s0, s59
	s_cselect_b64 s[14:15], -1, 0
	s_and_b64 vcc, exec, s[14:15]
	s_cbranch_vccnz .LBB0_904
	v_lshl_add_u64 v[60:61], v[210:211], 0, s[18:19]
	s_mov_b64 s[0:1], 0xba60000
	s_add_i32 s16, s60, s35
	v_lshl_add_u64 v[60:61], v[60:61], 0, s[0:1]
	s_mov_b32 s0, m0
	s_mov_b32 m0, s16
	s_nop 0
	global_load_lds_dwordx4 v[60:61], off
	s_mov_b32 m0, s0

.LBB0_906:
	v_max_f32_e32 v60, v97, v97
	v_max_f32_e32 v61, v96, v96
	v_max_f32_e32 v60, v61, v60
	v_max3_f32 v61, v98, v99, v81
	v_max3_f32 v60, v60, v80, v82
	v_max3_f32 v60, v60, v83, v100
	v_max3_f32 v61, v61, v102, v103
	v_max3_f32 v60, v60, v101, v84
	v_max3_f32 v61, v61, v86, v87
	v_max3_f32 v60, v60, v85, v104
	v_max3_f32 v61, v61, v106, v107
	v_max3_f32 v60, v60, v105, v88
	v_max3_f32 v61, v61, v90, v91
	v_max3_f32 v60, v60, v89, v108
	v_max3_f32 v61, v61, v110, v111
	v_max3_f32 v60, v60, v109, v92
	v_max3_f32 v61, v61, v94, v95
	v_max3_f32 v60, v60, v93, v61
	v_mov_b32_e32 v61, v60
	s_nop 1
	v_permlane32_swap_b32_e32 v60, v61
	v_max_f32_e32 v60, v60, v61
	v_cmp_lt_f32_e32 vcc, s34, v60
	s_cmp_lg_u64 vcc, 0
	v_add_f32_e32 v241, v241, v76
	s_cselect_b64 s[0:1], -1, 0
	s_cbranch_vccnz .LBB0_944

.LBB0_915:
	v_add_u32_e32 v228, s60, v240
	ds_read_b64_tr_b16 v[186:187], v228 offset:24576
	ds_read_b64_tr_b16 v[188:189], v228 offset:25088
	s_waitcnt lgkmcnt(9)
	v_mfma_f32_32x32x16_bf16 v[64:79], v[174:177], v[134:137], v[32:47]
	v_add_f32_e32 v48, v96, v97
	v_add_f32_e32 v48, v98, v48
	v_add_f32_e32 v48, v99, v48
	v_add_f32_e32 v48, v100, v48
	v_add_f32_e32 v48, v101, v48
	v_cvt_pk_bf16_f32 v142, v96, v97
	v_cvt_pk_bf16_f32 v143, v98, v99
	ds_read_b64_tr_b16 v[182:183], v228 offset:28672
	ds_read_b64_tr_b16 v[184:185], v228 offset:29184
	v_add_f32_e32 v48, v102, v48
	v_add_f32_e32 v48, v103, v48
	v_add_f32_e32 v48, v104, v48
	v_add_f32_e32 v96, v105, v48
	s_waitcnt lgkmcnt(10)
	v_mfma_f32_32x32x16_bf16 v[48:63], v[170:173], v[134:137], v[32:47]
	v_cvt_pk_bf16_f32 v144, v100, v101
	v_cvt_pk_bf16_f32 v145, v102, v103
	ds_read_b64_tr_b16 v[178:179], v228 offset:25600
	ds_read_b64_tr_b16 v[180:181], v228 offset:26112
	s_waitcnt lgkmcnt(11)
	v_mfma_f32_32x32x16_bf16 v[64:79], v[166:169], v[122:125], v[64:79]
	v_add_f32_e32 v96, v106, v96
	v_add_f32_e32 v96, v107, v96
	v_add_f32_e32 v96, v108, v96
	v_add_f32_e32 v96, v109, v96
	v_cvt_pk_bf16_f32 v138, v104, v105
	v_cvt_pk_bf16_f32 v139, v106, v107
	ds_read_b64_tr_b16 v[104:105], v228 offset:29696
	ds_read_b64_tr_b16 v[106:107], v228 offset:30208
	s_waitcnt lgkmcnt(12)
	v_mfma_f32_32x32x16_bf16 v[48:63], v[162:165], v[122:125], v[48:63]
	v_add_f32_e32 v96, v110, v96
	v_add_f32_e32 v96, v111, v96
	v_add_f32_e32 v96, v80, v96
	v_add_f32_e32 v96, v81, v96
	v_cvt_pk_bf16_f32 v140, v108, v109
	v_cvt_pk_bf16_f32 v141, v110, v111
	ds_read_b64_tr_b16 v[100:101], v228 offset:26624
	ds_read_b64_tr_b16 v[102:103], v228 offset:27136
	s_waitcnt lgkmcnt(13)
	v_mfma_f32_32x32x16_bf16 v[64:79], v[158:161], v[118:121], v[64:79]
	v_add_f32_e32 v96, v82, v96
	v_add_f32_e32 v96, v83, v96
	v_add_f32_e32 v96, v84, v96
	v_add_f32_e32 v108, v85, v96
	v_cvt_pk_bf16_f32 v130, v80, v81
	v_cvt_pk_bf16_f32 v131, v82, v83
	ds_read_b64_tr_b16 v[96:97], v228 offset:30720
	ds_read_b64_tr_b16 v[98:99], v228 offset:31232
	s_waitcnt lgkmcnt(14)
	v_mfma_f32_32x32x16_bf16 v[48:63], v[154:157], v[118:121], v[48:63]
	v_add_f32_e32 v80, v86, v108
	v_add_f32_e32 v80, v87, v80
	v_add_f32_e32 v80, v88, v80
	v_add_f32_e32 v80, v89, v80
	v_cvt_pk_bf16_f32 v132, v84, v85
	v_cvt_pk_bf16_f32 v133, v86, v87
	ds_read_b64_tr_b16 v[84:85], v228 offset:27648
	ds_read_b64_tr_b16 v[86:87], v228 offset:28160
	s_waitcnt lgkmcnt(14)
	v_mfma_f32_32x32x16_bf16 v[64:79], v[150:153], v[114:117], v[64:79]
	v_add_f32_e32 v80, v90, v80
	v_add_f32_e32 v80, v91, v80
	v_add_f32_e32 v80, v92, v80
	v_add_f32_e32 v108, v93, v80
	v_cvt_pk_bf16_f32 v126, v88, v89
	v_cvt_pk_bf16_f32 v127, v90, v91
	ds_read_b64_tr_b16 v[80:81], v228 offset:31744
	ds_read_b64_tr_b16 v[82:83], v228 offset:32256
	v_mfma_f32_32x32x16_bf16 v[48:63], v[146:149], v[114:117], v[48:63]
	v_add_f32_e32 v88, v94, v108
	v_add_f32_e32 v88, v95, v88
	v_cvt_pk_bf16_f32 v128, v92, v93
	v_cvt_pk_bf16_f32 v129, v94, v95
	s_add_i32 s62, s20, 2
	s_cmp_ge_u32 s62, s59
	s_cselect_b64 s[16:17], -1, 0
	s_and_b64 vcc, exec, s[16:17]
	s_cbranch_vccnz .LBB0_917
	v_lshl_add_u64 v[90:91], v[210:211], 0, s[18:19]
	s_add_i32 s0, s61, s35
	v_lshl_add_u64 v[90:91], v[90:91], 0, s[86:87]
	s_mov_b32 s1, m0
	s_mov_b32 m0, s0
	s_nop 0
	global_load_lds_dwordx4 v[90:91], off
	s_mov_b32 m0, s1

.LBB0_921:
	v_add_f32_e32 v241, v241, v88
	v_max_f32_e32 v88, v65, v65
	v_max_f32_e32 v89, v64, v64
	v_max_f32_e32 v88, v89, v88
	v_max3_f32 v89, v66, v67, v49
	v_max3_f32 v88, v88, v48, v50
	v_max3_f32 v88, v88, v51, v68
	v_max3_f32 v89, v89, v70, v71
	v_max3_f32 v88, v88, v69, v52
	v_max3_f32 v89, v89, v54, v55
	v_max3_f32 v88, v88, v53, v72
	v_max3_f32 v89, v89, v74, v75
	v_max3_f32 v88, v88, v73, v56
	v_max3_f32 v89, v89, v58, v59
	v_max3_f32 v88, v88, v57, v76
	v_max3_f32 v89, v89, v78, v79
	v_max3_f32 v88, v88, v77, v60
	v_max3_f32 v89, v89, v62, v63
	v_max3_f32 v88, v88, v61, v89
	v_mov_b32_e32 v89, v88
	s_nop 1
	v_permlane32_swap_b32_e32 v88, v89
	v_max_f32_e32 v88, v88, v89
	v_cmp_lt_f32_e32 vcc, s34, v88
	s_cmp_lg_u64 vcc, 0
	s_cselect_b64 s[20:21], -1, 0
	s_cbranch_vccnz .LBB0_947
